# gemm1: paired 256x128 tiles (two M-tiles share the B tile), BK=32 3-slot LDS ring, k-lo/k-hi halves of each 128-B line fetched back-to-back
# speedup vs baseline: 1.0078x; 1.0078x over previous
.LBB0_507:
	s_andn2_b64 vcc, exec, s[4:5]
	s_cbranch_vccnz .LBB0_534
	v_readlane_b32 s4, v255, 1
	s_cmp_gt_i32 s4, 0
	s_mov_b64 s[4:5], -1
	s_movk_i32 s31, 0x48
	s_cbranch_scc0 .LBB0_524
	s_mov_b32 s36, s22
	s_cmpk_gt_i32 s71, 0x7ff
	s_cbranch_scc1 .LBB0_523
	s_mov_b64 s[28:29], s[12:13]
	v_readlane_b32 s12, v252, 4
	s_mul_i32 s4, s36, 0x2580000
	v_readlane_b32 s26, v252, 18
	s_mul_hi_i32 s5, s36, 0x2580000
	v_readlane_b32 s13, v252, 5
	v_readlane_b32 s14, v252, 6
	v_readlane_b32 s15, v252, 7
	v_readlane_b32 s16, v252, 8
	v_readlane_b32 s18, v252, 10
	v_readlane_b32 s19, v252, 11
	v_readlane_b32 s24, v252, 16
	v_readlane_b32 s25, v252, 17
	v_readlane_b32 s27, v252, 19
	s_add_u32 s4, s26, s4
	s_mov_b64 s[12:13], s[28:29]
	s_mov_b32 s16, 0xfc2757d1
	s_mov_b32 s15, 0xf534ddc0
	s_mov_b32 s14, 0xdb629599
	s_mov_b32 s19, 0x80000
	s_mov_b32 s18, 0x10000
	s_addc_u32 s5, s27, s5
	s_lshl_b32 s24, s71, 1
	s_lshl_b32 s25, s71, 7
	s_mov_b32 s26, s71
	v_readlane_b32 s17, v252, 9
	v_readlane_b32 s20, v252, 12
	v_readlane_b32 s21, v252, 13
	v_readlane_b32 s22, v252, 14
	v_readlane_b32 s23, v252, 15
	s_branch .LBB0_513

.LBB0_512:
	v_lshrrev_b32_e32 v66, 3, v88
	v_and_or_b32 v66, v66, 4, v90
	s_movk_i32 s22, 0x110
	v_and_or_b32 v0, v88, 64, v0
	v_mul_lo_u32 v66, v66, s22
	v_cvt_pk_bf16_f32 v50, v50, s0
	v_lshl_add_u32 v0, v0, 1, v66
	v_cvt_pk_bf16_f32 v34, v34, s0
	v_cvt_pk_bf16_f32 v18, v18, s0
	v_cvt_pk_bf16_f32 v2, v2, s0
	ds_write_b16 v0, v50
	v_cvt_pk_bf16_f32 v50, v51, s0
	ds_write_b16 v0, v34 offset:64
	v_cvt_pk_bf16_f32 v34, v35, s0
	ds_write_b16 v0, v18 offset:8704
	v_cvt_pk_bf16_f32 v18, v19, s0
	ds_write_b16 v0, v2 offset:8768
	v_cvt_pk_bf16_f32 v2, v3, s0
	ds_write_b16 v0, v50 offset:272
	v_cvt_pk_bf16_f32 v50, v52, s0
	ds_write_b16 v0, v34 offset:336
	v_cvt_pk_bf16_f32 v34, v36, s0
	ds_write_b16 v0, v18 offset:8976
	v_cvt_pk_bf16_f32 v18, v20, s0
	ds_write_b16 v0, v2 offset:9040
	v_cvt_pk_bf16_f32 v2, v4, s0
	ds_write_b16 v0, v50 offset:544
	v_cvt_pk_bf16_f32 v50, v53, s0
	ds_write_b16 v0, v34 offset:608
	v_cvt_pk_bf16_f32 v34, v37, s0
	ds_write_b16 v0, v18 offset:9248
	v_cvt_pk_bf16_f32 v18, v21, s0
	ds_write_b16 v0, v2 offset:9312
	v_cvt_pk_bf16_f32 v2, v5, s0
	ds_write_b16 v0, v50 offset:816
	v_cvt_pk_bf16_f32 v50, v54, s0
	ds_write_b16 v0, v34 offset:880
	v_cvt_pk_bf16_f32 v34, v38, s0
	ds_write_b16 v0, v18 offset:9520
	v_cvt_pk_bf16_f32 v18, v22, s0
	ds_write_b16 v0, v2 offset:9584
	v_cvt_pk_bf16_f32 v2, v6, s0
	ds_write_b16 v0, v50 offset:2176
	v_cvt_pk_bf16_f32 v50, v55, s0
	ds_write_b16 v0, v34 offset:2240
	v_cvt_pk_bf16_f32 v34, v39, s0
	ds_write_b16 v0, v18 offset:10880
	v_cvt_pk_bf16_f32 v18, v23, s0
	ds_write_b16 v0, v2 offset:10944
	v_cvt_pk_bf16_f32 v2, v7, s0
	ds_write_b16 v0, v50 offset:2448
	v_cvt_pk_bf16_f32 v50, v56, s0
	ds_write_b16 v0, v34 offset:2512
	v_cvt_pk_bf16_f32 v34, v40, s0
	ds_write_b16 v0, v18 offset:11152
	v_cvt_pk_bf16_f32 v18, v24, s0
	ds_write_b16 v0, v2 offset:11216
	v_cvt_pk_bf16_f32 v2, v8, s0
	ds_write_b16 v0, v50 offset:2720
	v_cvt_pk_bf16_f32 v50, v57, s0
	ds_write_b16 v0, v34 offset:2784
	v_cvt_pk_bf16_f32 v34, v41, s0
	ds_write_b16 v0, v18 offset:11424
	v_cvt_pk_bf16_f32 v18, v25, s0
	ds_write_b16 v0, v2 offset:11488
	v_cvt_pk_bf16_f32 v2, v9, s0
	ds_write_b16 v0, v50 offset:2992
	v_cvt_pk_bf16_f32 v50, v58, s0
	ds_write_b16 v0, v34 offset:3056
	v_cvt_pk_bf16_f32 v34, v42, s0
	ds_write_b16 v0, v18 offset:11696
	v_cvt_pk_bf16_f32 v18, v26, s0
	ds_write_b16 v0, v2 offset:11760
	v_cvt_pk_bf16_f32 v2, v10, s0
	ds_write_b16 v0, v50 offset:4352
	v_cvt_pk_bf16_f32 v50, v59, s0
	ds_write_b16 v0, v34 offset:4416
	v_cvt_pk_bf16_f32 v34, v43, s0
	ds_write_b16 v0, v18 offset:13056
	v_cvt_pk_bf16_f32 v18, v27, s0
	ds_write_b16 v0, v2 offset:13120
	v_cvt_pk_bf16_f32 v2, v11, s0
	ds_write_b16 v0, v50 offset:4624
	v_cvt_pk_bf16_f32 v50, v60, s0
	ds_write_b16 v0, v34 offset:4688
	v_cvt_pk_bf16_f32 v34, v44, s0
	ds_write_b16 v0, v18 offset:13328
	v_cvt_pk_bf16_f32 v18, v28, s0
	ds_write_b16 v0, v2 offset:13392
	v_cvt_pk_bf16_f32 v2, v12, s0
	ds_write_b16 v0, v50 offset:4896
	v_cvt_pk_bf16_f32 v50, v61, s0
	ds_write_b16 v0, v34 offset:4960
	v_cvt_pk_bf16_f32 v34, v45, s0
	ds_write_b16 v0, v18 offset:13600
	v_cvt_pk_bf16_f32 v18, v29, s0
	ds_write_b16 v0, v2 offset:13664
	v_cvt_pk_bf16_f32 v2, v13, s0
	ds_write_b16 v0, v50 offset:5168
	v_cvt_pk_bf16_f32 v50, v62, s0
	ds_write_b16 v0, v34 offset:5232
	v_cvt_pk_bf16_f32 v34, v46, s0
	ds_write_b16 v0, v18 offset:13872
	v_cvt_pk_bf16_f32 v18, v30, s0
	ds_write_b16 v0, v2 offset:13936
	v_cvt_pk_bf16_f32 v2, v14, s0
	ds_write_b16 v0, v50 offset:6528
	v_cvt_pk_bf16_f32 v50, v63, s0
	ds_write_b16 v0, v34 offset:6592
	v_cvt_pk_bf16_f32 v34, v47, s0
	ds_write_b16 v0, v18 offset:15232
	v_cvt_pk_bf16_f32 v18, v31, s0
	ds_write_b16 v0, v2 offset:15296
	v_cvt_pk_bf16_f32 v2, v15, s0
	ds_write_b16 v0, v50 offset:6800
	v_cvt_pk_bf16_f32 v50, v64, s0
	ds_write_b16 v0, v34 offset:6864
	v_cvt_pk_bf16_f32 v34, v48, s0
	ds_write_b16 v0, v18 offset:15504
	v_cvt_pk_bf16_f32 v18, v32, s0
	ds_write_b16 v0, v2 offset:15568
	v_cvt_pk_bf16_f32 v2, v16, s0
	ds_write_b16 v0, v50 offset:7072
	v_cvt_pk_bf16_f32 v50, v65, s0
	ds_write_b16 v0, v34 offset:7136
	v_cvt_pk_bf16_f32 v34, v49, s0
	ds_write_b16 v0, v18 offset:15776
	v_cvt_pk_bf16_f32 v18, v33, s0
	ds_write_b16 v0, v2 offset:15840
	v_cvt_pk_bf16_f32 v2, v17, s0
	ds_write_b16 v0, v50 offset:7344
	ds_write_b16 v0, v34 offset:7408
	ds_write_b16 v0, v18 offset:16048
	ds_write_b16 v0, v2 offset:16112
	v_ashrrev_i32_e32 v0, 4, v88
	v_and_b32_e32 v6, 0x78, v89
	v_add_u32_e32 v7, s27, v0
	v_mul_lo_u32 v0, v0, s22
	v_lshl_add_u32 v12, v6, 1, v0
	s_waitcnt lgkmcnt(0)
	s_barrier
	ds_read_b128 v[2:5], v12
	v_mul_lo_u32 v0, s29, v7
	v_add3_u32 v0, s28, v6, v0
	v_lshl_add_u64 v[10:11], v[0:1], 1, s[20:21]
	ds_read_b128 v[6:9], v12 offset:4352
	s_waitcnt lgkmcnt(1)
	global_store_dwordx4 v[10:11], v[2:5], off
	ds_read_b128 v[2:5], v12 offset:8704
	s_lshl_b32 s22, s29, 4
	v_add_u32_e32 v0, s22, v0
	v_lshl_add_u64 v[10:11], v[0:1], 1, s[20:21]
	v_add_u32_e32 v0, s22, v0
	s_waitcnt lgkmcnt(1)
	global_store_dwordx4 v[10:11], v[6:9], off
	v_lshl_add_u64 v[10:11], v[0:1], 1, s[20:21]
	ds_read_b128 v[6:9], v12 offset:13056
	s_waitcnt lgkmcnt(1)
	global_store_dwordx4 v[10:11], v[2:5], off
	ds_read_b128 v[2:5], v12 offset:17408
	v_add_u32_e32 v0, s22, v0
	v_lshl_add_u64 v[10:11], v[0:1], 1, s[20:21]
	v_add_u32_e32 v0, s22, v0
	s_waitcnt lgkmcnt(1)
	global_store_dwordx4 v[10:11], v[6:9], off
	v_lshl_add_u64 v[10:11], v[0:1], 1, s[20:21]
	ds_read_b128 v[6:9], v12 offset:21760
	s_waitcnt lgkmcnt(1)
	global_store_dwordx4 v[10:11], v[2:5], off
	ds_read_b128 v[2:5], v12 offset:26112
	v_add_u32_e32 v0, s22, v0
	v_lshl_add_u64 v[10:11], v[0:1], 1, s[20:21]
	v_add_u32_e32 v0, s22, v0
	s_waitcnt lgkmcnt(1)
	global_store_dwordx4 v[10:11], v[6:9], off
	v_lshl_add_u64 v[10:11], v[0:1], 1, s[20:21]
	ds_read_b128 v[6:9], v12 offset:30464
	v_add_u32_e32 v0, s22, v0
	s_waitcnt lgkmcnt(1)
	global_store_dwordx4 v[10:11], v[2:5], off
	s_nop 1
	v_lshl_add_u64 v[2:3], v[0:1], 1, s[20:21]
	s_waitcnt lgkmcnt(0)
	global_store_dwordx4 v[2:3], v[6:9], off
	s_cmp_eq_u32 m0, 0x7ead
	s_cbranch_scc0 .Lg1p_next
	s_mov_b32 m0, 0
	s_nop 1
	v_mov_b32_e32 v50, v94
	v_mov_b32_e32 v51, v95
	v_mov_b32_e32 v52, v96
	v_mov_b32_e32 v53, v97
	v_mov_b32_e32 v54, v98
	v_mov_b32_e32 v55, v99
	v_mov_b32_e32 v56, v100
	v_mov_b32_e32 v57, v101
	v_mov_b32_e32 v58, v102
	v_mov_b32_e32 v59, v103
	v_mov_b32_e32 v60, v104
	v_mov_b32_e32 v61, v105
	v_mov_b32_e32 v62, v106
	v_mov_b32_e32 v63, v107
	v_mov_b32_e32 v64, v108
	v_mov_b32_e32 v65, v109
	v_mov_b32_e32 v34, v110
	v_mov_b32_e32 v35, v111
	v_mov_b32_e32 v36, v112
	v_mov_b32_e32 v37, v113
	v_mov_b32_e32 v38, v114
	v_mov_b32_e32 v39, v115
	v_mov_b32_e32 v40, v116
	v_mov_b32_e32 v41, v117
	v_mov_b32_e32 v42, v118
	v_mov_b32_e32 v43, v119
	v_mov_b32_e32 v44, v120
	v_mov_b32_e32 v45, v121
	v_mov_b32_e32 v46, v122
	v_mov_b32_e32 v47, v123
	v_mov_b32_e32 v48, v124
	v_mov_b32_e32 v49, v125
	v_mov_b32_e32 v18, v134
	v_mov_b32_e32 v19, v135
	v_mov_b32_e32 v20, v136
	v_mov_b32_e32 v21, v137
	v_mov_b32_e32 v22, v138
	v_mov_b32_e32 v23, v139
	v_mov_b32_e32 v24, v140
	v_mov_b32_e32 v25, v141
	v_mov_b32_e32 v26, v142
	v_mov_b32_e32 v27, v143
	v_mov_b32_e32 v28, v144
	v_mov_b32_e32 v29, v145
	v_mov_b32_e32 v30, v146
	v_mov_b32_e32 v31, v147
	v_mov_b32_e32 v32, v148
	v_mov_b32_e32 v33, v149
	v_mov_b32_e32 v2, v150
	v_mov_b32_e32 v3, v151
	v_mov_b32_e32 v4, v152
	v_mov_b32_e32 v5, v153
	v_mov_b32_e32 v6, v154
	v_mov_b32_e32 v7, v155
	v_mov_b32_e32 v8, v156
	v_mov_b32_e32 v9, v157
	v_mov_b32_e32 v10, v158
	v_mov_b32_e32 v11, v159
	v_mov_b32_e32 v12, v160
	v_mov_b32_e32 v13, v161
	v_mov_b32_e32 v14, v162
	v_mov_b32_e32 v15, v163
	v_mov_b32_e32 v16, v164
	v_mov_b32_e32 v17, v165
	v_and_b32_e32 v0, 31, v88
	s_add_i32 s27, s27, 0x80
	s_and_b32 s28, s25, 0x1f80
	s_branch .Lg1p_epi
.Lg1p_next:
	s_add_i32 s26, s26, s81
	v_readlane_b32 s20, v254, 40
	s_add_i32 s24, s24, s20
	v_readlane_b32 s20, v254, 37
	s_add_i32 s25, s25, s20
	s_cmpk_gt_i32 s26, 0x7ff
	s_cbranch_scc1 .LBB0_523
.LBB0_513:
	v_mov_b32_e32 v0, v1
	s_and_b32 s28, s25, 0x1f80
	v_mbcnt_lo_u32_b32 v0, -1, v0
	v_mbcnt_hi_u32_b32 v0, -1, v0
	v_add_u32_e32 v88, s80, v0
	s_lshl_b32 s27, s24, 1
	s_and_b32 s27, s27, 0xffffff00
	s_waitcnt lgkmcnt(0)
	v_lshlrev_b32_e32 v89, 3, v88
	v_lshrrev_b32_e32 v84, 2, v88
	v_lshrrev_b32_e32 v85, 6, v88
	v_lshl_add_u32 v84, v85, 4, v84
	v_bfe_u32 v85, v88, 4, 2
	v_and_b32_e32 v86, 3, v88
	v_xor_b32_e32 v85, v85, v86
	v_lshlrev_b32_e32 v85, 4, v85
	v_add_u32_e32 v86, s27, v84
	v_lshl_or_b32 v66, v86, 11, v85
	v_add_u32_e32 v68, 0x8000, v66
	v_add_u32_e32 v70, 0x40000, v66
	v_add_u32_e32 v72, 0x48000, v66
	v_add_u32_e32 v86, s28, v84
	v_lshl_or_b32 v74, v86, 11, v85
	v_add_u32_e32 v76, 0x8000, v74
	v_mov_b32_e32 v67, 0
	v_mov_b32_e32 v69, 0
	v_mov_b32_e32 v71, 0
	v_mov_b32_e32 v73, 0
	v_mov_b32_e32 v75, 0
	v_mov_b32_e32 v77, 0
	v_lshl_add_u64 v[66:67], v[66:67], 0, s[72:73]
	v_lshl_add_u64 v[68:69], v[68:69], 0, s[72:73]
	v_lshl_add_u64 v[70:71], v[70:71], 0, s[72:73]
	v_lshl_add_u64 v[72:73], v[72:73], 0, s[72:73]
	v_lshl_add_u64 v[74:75], v[74:75], 0, s[4:5]
	v_lshl_add_u64 v[76:77], v[76:77], 0, s[4:5]
	v_mov_b32_e32 v84, 64
	v_mov_b32_e32 v85, 0
	v_lshl_add_u64 v[126:127], v[66:67], 0, v[84:85]
	v_lshl_add_u64 v[128:129], v[68:69], 0, v[84:85]
	v_lshl_add_u64 v[130:131], v[70:71], 0, v[84:85]
	v_lshl_add_u64 v[132:133], v[72:73], 0, v[84:85]
	v_lshl_add_u64 v[244:245], v[74:75], 0, v[84:85]
	v_lshl_add_u64 v[246:247], v[76:77], 0, v[84:85]
	v_bfe_u32 v84, v88, 5, 1
	v_bfe_u32 v85, v88, 2, 2
	v_xor_b32_e32 v84, v84, v85
	v_lshlrev_b32_e32 v84, 4, v84
	v_lshrrev_b32_e32 v85, 1, v88
	v_and_b32_e32 v85, 64, v85
	v_and_b32_e32 v86, 31, v88
	v_or_b32_e32 v85, v85, v86
	v_lshl_or_b32 v78, v85, 6, v84
	v_xor_b32_e32 v79, 32, v78
	v_and_b32_e32 v85, 0x5f, v88
	v_lshl_or_b32 v80, v85, 6, v84
	v_add_u32_e32 v80, 0x4000, v80
	v_xor_b32_e32 v81, 32, v80
	v_mov_b32_e32 v82, 0x80
	v_mov_b32_e32 v83, 0
	s_lshl_b32 vcc_lo, s80, 5
	v_ashrrev_i32_e32 v2, 1, v88
	v_and_b32_e32 v90, 0xffffffc0, v2
	v_and_b32_e32 v0, 31, v88
	v_mov_b32_e32 v50, 0
	v_mov_b32_e32 v51, 0
	v_mov_b32_e32 v52, 0
	v_mov_b32_e32 v53, 0
	v_mov_b32_e32 v54, 0
	v_mov_b32_e32 v55, 0
	v_mov_b32_e32 v56, 0
	v_mov_b32_e32 v57, 0
	v_mov_b32_e32 v58, 0
	v_mov_b32_e32 v59, 0
	v_mov_b32_e32 v60, 0
	v_mov_b32_e32 v61, 0
	v_mov_b32_e32 v62, 0
	v_mov_b32_e32 v63, 0
	v_mov_b32_e32 v64, 0
	v_mov_b32_e32 v65, 0
	v_mov_b32_e32 v34, 0
	v_mov_b32_e32 v35, 0
	v_mov_b32_e32 v36, 0
	v_mov_b32_e32 v37, 0
	v_mov_b32_e32 v38, 0
	v_mov_b32_e32 v39, 0
	v_mov_b32_e32 v40, 0
	v_mov_b32_e32 v41, 0
	v_mov_b32_e32 v42, 0
	v_mov_b32_e32 v43, 0
	v_mov_b32_e32 v44, 0
	v_mov_b32_e32 v45, 0
	v_mov_b32_e32 v46, 0
	v_mov_b32_e32 v47, 0
	v_mov_b32_e32 v48, 0
	v_mov_b32_e32 v49, 0
	v_mov_b32_e32 v18, 0
	v_mov_b32_e32 v19, 0
	v_mov_b32_e32 v20, 0
	v_mov_b32_e32 v21, 0
	v_mov_b32_e32 v22, 0
	v_mov_b32_e32 v23, 0
	v_mov_b32_e32 v24, 0
	v_mov_b32_e32 v25, 0
	v_mov_b32_e32 v26, 0
	v_mov_b32_e32 v27, 0
	v_mov_b32_e32 v28, 0
	v_mov_b32_e32 v29, 0
	v_mov_b32_e32 v30, 0
	v_mov_b32_e32 v31, 0
	v_mov_b32_e32 v32, 0
	v_mov_b32_e32 v33, 0
	v_mov_b32_e32 v2, 0
	v_mov_b32_e32 v3, 0
	v_mov_b32_e32 v4, 0
	v_mov_b32_e32 v5, 0
	v_mov_b32_e32 v6, 0
	v_mov_b32_e32 v7, 0
	v_mov_b32_e32 v8, 0
	v_mov_b32_e32 v9, 0
	v_mov_b32_e32 v10, 0
	v_mov_b32_e32 v11, 0
	v_mov_b32_e32 v12, 0
	v_mov_b32_e32 v13, 0
	v_mov_b32_e32 v14, 0
	v_mov_b32_e32 v15, 0
	v_mov_b32_e32 v16, 0
	v_mov_b32_e32 v17, 0
	v_mov_b32_e32 v94, 0
	v_mov_b32_e32 v95, 0
	v_mov_b32_e32 v96, 0
	v_mov_b32_e32 v97, 0
	v_mov_b32_e32 v98, 0
	v_mov_b32_e32 v99, 0
	v_mov_b32_e32 v100, 0
	v_mov_b32_e32 v101, 0
	v_mov_b32_e32 v102, 0
	v_mov_b32_e32 v103, 0
	v_mov_b32_e32 v104, 0
	v_mov_b32_e32 v105, 0
	v_mov_b32_e32 v106, 0
	v_mov_b32_e32 v107, 0
	v_mov_b32_e32 v108, 0
	v_mov_b32_e32 v109, 0
	v_mov_b32_e32 v110, 0
	v_mov_b32_e32 v111, 0
	v_mov_b32_e32 v112, 0
	v_mov_b32_e32 v113, 0
	v_mov_b32_e32 v114, 0
	v_mov_b32_e32 v115, 0
	v_mov_b32_e32 v116, 0
	v_mov_b32_e32 v117, 0
	v_mov_b32_e32 v118, 0
	v_mov_b32_e32 v119, 0
	v_mov_b32_e32 v120, 0
	v_mov_b32_e32 v121, 0
	v_mov_b32_e32 v122, 0
	v_mov_b32_e32 v123, 0
	v_mov_b32_e32 v124, 0
	v_mov_b32_e32 v125, 0
	v_mov_b32_e32 v134, 0
	v_mov_b32_e32 v135, 0
	v_mov_b32_e32 v136, 0
	v_mov_b32_e32 v137, 0
	v_mov_b32_e32 v138, 0
	v_mov_b32_e32 v139, 0
	v_mov_b32_e32 v140, 0
	v_mov_b32_e32 v141, 0
	v_mov_b32_e32 v142, 0
	v_mov_b32_e32 v143, 0
	v_mov_b32_e32 v144, 0
	v_mov_b32_e32 v145, 0
	v_mov_b32_e32 v146, 0
	v_mov_b32_e32 v147, 0
	v_mov_b32_e32 v148, 0
	v_mov_b32_e32 v149, 0
	v_mov_b32_e32 v150, 0
	v_mov_b32_e32 v151, 0
	v_mov_b32_e32 v152, 0
	v_mov_b32_e32 v153, 0
	v_mov_b32_e32 v154, 0
	v_mov_b32_e32 v155, 0
	v_mov_b32_e32 v156, 0
	v_mov_b32_e32 v157, 0
	v_mov_b32_e32 v158, 0
	v_mov_b32_e32 v159, 0
	v_mov_b32_e32 v160, 0
	v_mov_b32_e32 v161, 0
	v_mov_b32_e32 v162, 0
	v_mov_b32_e32 v163, 0
	v_mov_b32_e32 v164, 0
	v_mov_b32_e32 v165, 0
	s_barrier
	s_mov_b32 m0, vcc_lo
	s_nop 0
	global_load_lds_dwordx4 v[66:67], off
	s_add_u32 m0, vcc_lo, 0x6000
	s_nop 0
	global_load_lds_dwordx4 v[126:127], off
	s_add_u32 m0, vcc_lo, 0x400
	s_nop 0
	global_load_lds_dwordx4 v[68:69], off
	s_add_u32 m0, vcc_lo, 0x6400
	s_nop 0
	global_load_lds_dwordx4 v[128:129], off
	s_add_u32 m0, vcc_lo, 0x2000
	s_nop 0
	global_load_lds_dwordx4 v[70:71], off
	s_add_u32 m0, vcc_lo, 0x8000
	s_nop 0
	global_load_lds_dwordx4 v[130:131], off
	s_add_u32 m0, vcc_lo, 0x2400
	s_nop 0
	global_load_lds_dwordx4 v[72:73], off
	s_add_u32 m0, vcc_lo, 0x8400
	s_nop 0
	global_load_lds_dwordx4 v[132:133], off
	s_add_u32 m0, vcc_lo, 0x4000
	s_nop 0
	global_load_lds_dwordx4 v[74:75], off
	s_add_u32 m0, vcc_lo, 0xa000
	s_nop 0
	global_load_lds_dwordx4 v[244:245], off
	s_add_u32 m0, vcc_lo, 0x4400
	s_nop 0
	global_load_lds_dwordx4 v[76:77], off
	s_add_u32 m0, vcc_lo, 0xa400
	s_nop 0
	global_load_lds_dwordx4 v[246:247], off
	v_lshl_add_u64 v[66:67], v[66:67], 0, v[82:83]
	v_lshl_add_u64 v[68:69], v[68:69], 0, v[82:83]
	v_lshl_add_u64 v[70:71], v[70:71], 0, v[82:83]
	v_lshl_add_u64 v[72:73], v[72:73], 0, v[82:83]
	v_lshl_add_u64 v[74:75], v[74:75], 0, v[82:83]
	v_lshl_add_u64 v[76:77], v[76:77], 0, v[82:83]
	v_lshl_add_u64 v[126:127], v[126:127], 0, v[82:83]
	v_lshl_add_u64 v[128:129], v[128:129], 0, v[82:83]
	v_lshl_add_u64 v[130:131], v[130:131], 0, v[82:83]
	v_lshl_add_u64 v[132:133], v[132:133], 0, v[82:83]
	v_lshl_add_u64 v[244:245], v[244:245], 0, v[82:83]
	v_lshl_add_u64 v[246:247], v[246:247], 0, v[82:83]
	s_waitcnt vmcnt(0)
	s_barrier
	ds_read_b128 v[166:169], v78
	ds_read_b128 v[170:173], v80
	ds_read_b128 v[174:177], v80 offset:2048
	ds_read_b128 v[178:181], v78 offset:2048
	ds_read_b128 v[182:185], v78 offset:8192
	ds_read_b128 v[188:191], v78 offset:10240
	s_waitcnt lgkmcnt(4)
	v_mfma_f32_32x32x16_bf16 v[50:65], v[166:169], v[170:173], v[50:65]
	ds_read_b128 v[192:195], v79
	s_waitcnt lgkmcnt(4)
	v_mfma_f32_32x32x16_bf16 v[34:49], v[166:169], v[174:177], v[34:49]
	ds_read_b128 v[206:209], v81
	s_waitcnt lgkmcnt(4)
	v_mfma_f32_32x32x16_bf16 v[18:33], v[178:181], v[170:173], v[18:33]
	ds_read_b128 v[210:213], v81 offset:2048
	v_mfma_f32_32x32x16_bf16 v[2:17], v[178:181], v[174:177], v[2:17]
	ds_read_b128 v[222:225], v79 offset:2048
	s_waitcnt lgkmcnt(5)
	v_mfma_f32_32x32x16_bf16 v[94:109], v[182:185], v[170:173], v[94:109]
	ds_read_b128 v[236:239], v79 offset:8192
	v_mfma_f32_32x32x16_bf16 v[110:125], v[182:185], v[174:177], v[110:125]
	ds_read_b128 v[240:243], v79 offset:10240
	s_waitcnt lgkmcnt(6)
	v_mfma_f32_32x32x16_bf16 v[134:149], v[188:191], v[170:173], v[134:149]
	v_mfma_f32_32x32x16_bf16 v[150:165], v[188:191], v[174:177], v[150:165]
	s_waitcnt vmcnt(0) lgkmcnt(0)
	s_barrier
	s_mov_b32 vcc_hi, 4
.Lg_gemm1p_loop:
	v_mfma_f32_32x32x16_bf16 v[50:65], v[192:195], v[206:209], v[50:65]
	s_add_u32 m0, vcc_lo, 0xc000
	ds_read_b128 v[166:169], v78 offset:24576
	global_load_lds_dwordx4 v[66:67], off
	v_mfma_f32_32x32x16_bf16 v[34:49], v[192:195], v[210:213], v[34:49]
	s_mov_b32 m0, vcc_lo
	ds_read_b128 v[170:173], v80 offset:24576
	global_load_lds_dwordx4 v[126:127], off
	v_mfma_f32_32x32x16_bf16 v[18:33], v[222:225], v[206:209], v[18:33]
	s_add_u32 m0, vcc_lo, 0xc400
	ds_read_b128 v[174:177], v80 offset:26624
	global_load_lds_dwordx4 v[68:69], off
	v_mfma_f32_32x32x16_bf16 v[2:17], v[222:225], v[210:213], v[2:17]
	s_add_u32 m0, vcc_lo, 0x400
	ds_read_b128 v[178:181], v78 offset:26624
	global_load_lds_dwordx4 v[128:129], off
	v_mfma_f32_32x32x16_bf16 v[94:109], v[236:239], v[206:209], v[94:109]
	s_add_u32 m0, vcc_lo, 0xe000
	ds_read_b128 v[182:185], v78 offset:32768
	global_load_lds_dwordx4 v[70:71], off
	v_mfma_f32_32x32x16_bf16 v[110:125], v[236:239], v[210:213], v[110:125]
	s_add_u32 m0, vcc_lo, 0x2000
	ds_read_b128 v[188:191], v78 offset:34816
	global_load_lds_dwordx4 v[130:131], off
	v_mfma_f32_32x32x16_bf16 v[134:149], v[240:243], v[206:209], v[134:149]
	s_add_u32 m0, vcc_lo, 0xe400
	s_nop 0
	global_load_lds_dwordx4 v[72:73], off
	v_mfma_f32_32x32x16_bf16 v[150:165], v[240:243], v[210:213], v[150:165]
	s_add_u32 m0, vcc_lo, 0x2400
	s_nop 0
	global_load_lds_dwordx4 v[132:133], off
	s_waitcnt lgkmcnt(4)
	v_mfma_f32_32x32x16_bf16 v[50:65], v[166:169], v[170:173], v[50:65]
	s_add_u32 m0, vcc_lo, 0x10000
	ds_read_b128 v[192:195], v79 offset:24576
	global_load_lds_dwordx4 v[74:75], off
	s_waitcnt lgkmcnt(4)
	v_mfma_f32_32x32x16_bf16 v[34:49], v[166:169], v[174:177], v[34:49]
	s_add_u32 m0, vcc_lo, 0x4000
	ds_read_b128 v[206:209], v81 offset:24576
	global_load_lds_dwordx4 v[244:245], off
	s_waitcnt lgkmcnt(4)
	v_mfma_f32_32x32x16_bf16 v[18:33], v[178:181], v[170:173], v[18:33]
	s_add_u32 m0, vcc_lo, 0x10400
	ds_read_b128 v[210:213], v81 offset:26624
	global_load_lds_dwordx4 v[76:77], off
	v_mfma_f32_32x32x16_bf16 v[2:17], v[178:181], v[174:177], v[2:17]
	s_add_u32 m0, vcc_lo, 0x4400
	ds_read_b128 v[222:225], v79 offset:26624
	global_load_lds_dwordx4 v[246:247], off
	s_waitcnt lgkmcnt(5)
	v_mfma_f32_32x32x16_bf16 v[94:109], v[182:185], v[170:173], v[94:109]
	ds_read_b128 v[236:239], v79 offset:32768
	v_lshl_add_u64 v[66:67], v[66:67], 0, v[82:83]
	v_lshl_add_u64 v[68:69], v[68:69], 0, v[82:83]
	v_lshl_add_u64 v[70:71], v[70:71], 0, v[82:83]
	v_lshl_add_u64 v[72:73], v[72:73], 0, v[82:83]
	v_lshl_add_u64 v[74:75], v[74:75], 0, v[82:83]
	v_lshl_add_u64 v[76:77], v[76:77], 0, v[82:83]
	v_lshl_add_u64 v[126:127], v[126:127], 0, v[82:83]
	v_lshl_add_u64 v[128:129], v[128:129], 0, v[82:83]
	v_lshl_add_u64 v[130:131], v[130:131], 0, v[82:83]
	v_lshl_add_u64 v[132:133], v[132:133], 0, v[82:83]
	v_lshl_add_u64 v[244:245], v[244:245], 0, v[82:83]
	v_lshl_add_u64 v[246:247], v[246:247], 0, v[82:83]
	v_mfma_f32_32x32x16_bf16 v[110:125], v[182:185], v[174:177], v[110:125]
	ds_read_b128 v[240:243], v79 offset:34816
	s_waitcnt lgkmcnt(6)
	v_mfma_f32_32x32x16_bf16 v[134:149], v[188:191], v[170:173], v[134:149]
	v_mfma_f32_32x32x16_bf16 v[150:165], v[188:191], v[174:177], v[150:165]
	s_waitcnt vmcnt(0) lgkmcnt(0)
	s_barrier
	v_mfma_f32_32x32x16_bf16 v[50:65], v[192:195], v[206:209], v[50:65]
	ds_read_b128 v[166:169], v78 offset:49152
	v_mfma_f32_32x32x16_bf16 v[34:49], v[192:195], v[210:213], v[34:49]
	ds_read_b128 v[170:173], v80 offset:49152
	v_mfma_f32_32x32x16_bf16 v[18:33], v[222:225], v[206:209], v[18:33]
	ds_read_b128 v[174:177], v80 offset:51200
	v_mfma_f32_32x32x16_bf16 v[2:17], v[222:225], v[210:213], v[2:17]
	ds_read_b128 v[178:181], v78 offset:51200
	v_mfma_f32_32x32x16_bf16 v[94:109], v[236:239], v[206:209], v[94:109]
	ds_read_b128 v[182:185], v78 offset:57344
	v_mfma_f32_32x32x16_bf16 v[110:125], v[236:239], v[210:213], v[110:125]
	ds_read_b128 v[188:191], v78 offset:59392
	v_mfma_f32_32x32x16_bf16 v[134:149], v[240:243], v[206:209], v[134:149]
	v_mfma_f32_32x32x16_bf16 v[150:165], v[240:243], v[210:213], v[150:165]
	s_waitcnt lgkmcnt(4)
	v_mfma_f32_32x32x16_bf16 v[50:65], v[166:169], v[170:173], v[50:65]
	ds_read_b128 v[192:195], v79 offset:49152
	s_waitcnt lgkmcnt(4)
	v_mfma_f32_32x32x16_bf16 v[34:49], v[166:169], v[174:177], v[34:49]
	ds_read_b128 v[206:209], v81 offset:49152
	s_waitcnt lgkmcnt(4)
	v_mfma_f32_32x32x16_bf16 v[18:33], v[178:181], v[170:173], v[18:33]
	ds_read_b128 v[210:213], v81 offset:51200
	v_mfma_f32_32x32x16_bf16 v[2:17], v[178:181], v[174:177], v[2:17]
	ds_read_b128 v[222:225], v79 offset:51200
	s_waitcnt lgkmcnt(5)
	v_mfma_f32_32x32x16_bf16 v[94:109], v[182:185], v[170:173], v[94:109]
	ds_read_b128 v[236:239], v79 offset:57344
	v_mfma_f32_32x32x16_bf16 v[110:125], v[182:185], v[174:177], v[110:125]
	ds_read_b128 v[240:243], v79 offset:59392
	s_waitcnt lgkmcnt(6)
	v_mfma_f32_32x32x16_bf16 v[134:149], v[188:191], v[170:173], v[134:149]
	v_mfma_f32_32x32x16_bf16 v[150:165], v[188:191], v[174:177], v[150:165]
	s_waitcnt vmcnt(0) lgkmcnt(0)
	s_barrier
	v_mfma_f32_32x32x16_bf16 v[50:65], v[192:195], v[206:209], v[50:65]
	s_add_u32 m0, vcc_lo, 0x6000
	ds_read_b128 v[166:169], v78
	global_load_lds_dwordx4 v[66:67], off
	v_mfma_f32_32x32x16_bf16 v[34:49], v[192:195], v[210:213], v[34:49]
	s_add_u32 m0, vcc_lo, 0xc000
	ds_read_b128 v[170:173], v80
	global_load_lds_dwordx4 v[126:127], off
	v_mfma_f32_32x32x16_bf16 v[18:33], v[222:225], v[206:209], v[18:33]
	s_add_u32 m0, vcc_lo, 0x6400
	ds_read_b128 v[174:177], v80 offset:2048
	global_load_lds_dwordx4 v[68:69], off
	v_mfma_f32_32x32x16_bf16 v[2:17], v[222:225], v[210:213], v[2:17]
	s_add_u32 m0, vcc_lo, 0xc400
	ds_read_b128 v[178:181], v78 offset:2048
	global_load_lds_dwordx4 v[128:129], off
	v_mfma_f32_32x32x16_bf16 v[94:109], v[236:239], v[206:209], v[94:109]
	s_add_u32 m0, vcc_lo, 0x8000
	ds_read_b128 v[182:185], v78 offset:8192
	global_load_lds_dwordx4 v[70:71], off
	v_mfma_f32_32x32x16_bf16 v[110:125], v[236:239], v[210:213], v[110:125]
	s_add_u32 m0, vcc_lo, 0xe000
	ds_read_b128 v[188:191], v78 offset:10240
	global_load_lds_dwordx4 v[130:131], off
	v_mfma_f32_32x32x16_bf16 v[134:149], v[240:243], v[206:209], v[134:149]
	s_add_u32 m0, vcc_lo, 0x8400
	s_nop 0
	global_load_lds_dwordx4 v[72:73], off
	v_mfma_f32_32x32x16_bf16 v[150:165], v[240:243], v[210:213], v[150:165]
	s_add_u32 m0, vcc_lo, 0xe400
	s_nop 0
	global_load_lds_dwordx4 v[132:133], off
	s_waitcnt lgkmcnt(4)
	v_mfma_f32_32x32x16_bf16 v[50:65], v[166:169], v[170:173], v[50:65]
	s_add_u32 m0, vcc_lo, 0xa000
	ds_read_b128 v[192:195], v79
	global_load_lds_dwordx4 v[74:75], off
	s_waitcnt lgkmcnt(4)
	v_mfma_f32_32x32x16_bf16 v[34:49], v[166:169], v[174:177], v[34:49]
	s_add_u32 m0, vcc_lo, 0x10000
	ds_read_b128 v[206:209], v81
	global_load_lds_dwordx4 v[244:245], off
	s_waitcnt lgkmcnt(4)
	v_mfma_f32_32x32x16_bf16 v[18:33], v[178:181], v[170:173], v[18:33]
	s_add_u32 m0, vcc_lo, 0xa400
	ds_read_b128 v[210:213], v81 offset:2048
	global_load_lds_dwordx4 v[76:77], off
	v_mfma_f32_32x32x16_bf16 v[2:17], v[178:181], v[174:177], v[2:17]
	s_add_u32 m0, vcc_lo, 0x10400
	ds_read_b128 v[222:225], v79 offset:2048
	global_load_lds_dwordx4 v[246:247], off
	s_waitcnt lgkmcnt(5)
	v_mfma_f32_32x32x16_bf16 v[94:109], v[182:185], v[170:173], v[94:109]
	ds_read_b128 v[236:239], v79 offset:8192
	v_lshl_add_u64 v[66:67], v[66:67], 0, v[82:83]
	v_lshl_add_u64 v[68:69], v[68:69], 0, v[82:83]
	v_lshl_add_u64 v[70:71], v[70:71], 0, v[82:83]
	v_lshl_add_u64 v[72:73], v[72:73], 0, v[82:83]
	v_lshl_add_u64 v[74:75], v[74:75], 0, v[82:83]
	v_lshl_add_u64 v[76:77], v[76:77], 0, v[82:83]
	v_lshl_add_u64 v[126:127], v[126:127], 0, v[82:83]
	v_lshl_add_u64 v[128:129], v[128:129], 0, v[82:83]
	v_lshl_add_u64 v[130:131], v[130:131], 0, v[82:83]
	v_lshl_add_u64 v[132:133], v[132:133], 0, v[82:83]
	v_lshl_add_u64 v[244:245], v[244:245], 0, v[82:83]
	v_lshl_add_u64 v[246:247], v[246:247], 0, v[82:83]
	v_mfma_f32_32x32x16_bf16 v[110:125], v[182:185], v[174:177], v[110:125]
	ds_read_b128 v[240:243], v79 offset:10240
	s_waitcnt lgkmcnt(6)
	v_mfma_f32_32x32x16_bf16 v[134:149], v[188:191], v[170:173], v[134:149]
	v_mfma_f32_32x32x16_bf16 v[150:165], v[188:191], v[174:177], v[150:165]
	s_waitcnt vmcnt(0) lgkmcnt(0)
	s_barrier
	v_mfma_f32_32x32x16_bf16 v[50:65], v[192:195], v[206:209], v[50:65]
	ds_read_b128 v[166:169], v78 offset:24576
	v_mfma_f32_32x32x16_bf16 v[34:49], v[192:195], v[210:213], v[34:49]
	ds_read_b128 v[170:173], v80 offset:24576
	v_mfma_f32_32x32x16_bf16 v[18:33], v[222:225], v[206:209], v[18:33]
	ds_read_b128 v[174:177], v80 offset:26624
	v_mfma_f32_32x32x16_bf16 v[2:17], v[222:225], v[210:213], v[2:17]
	ds_read_b128 v[178:181], v78 offset:26624
	v_mfma_f32_32x32x16_bf16 v[94:109], v[236:239], v[206:209], v[94:109]
	ds_read_b128 v[182:185], v78 offset:32768
	v_mfma_f32_32x32x16_bf16 v[110:125], v[236:239], v[210:213], v[110:125]
	ds_read_b128 v[188:191], v78 offset:34816
	v_mfma_f32_32x32x16_bf16 v[134:149], v[240:243], v[206:209], v[134:149]
	v_mfma_f32_32x32x16_bf16 v[150:165], v[240:243], v[210:213], v[150:165]
	s_waitcnt lgkmcnt(4)
	v_mfma_f32_32x32x16_bf16 v[50:65], v[166:169], v[170:173], v[50:65]
	ds_read_b128 v[192:195], v79 offset:24576
	s_waitcnt lgkmcnt(4)
	v_mfma_f32_32x32x16_bf16 v[34:49], v[166:169], v[174:177], v[34:49]
	ds_read_b128 v[206:209], v81 offset:24576
	s_waitcnt lgkmcnt(4)
	v_mfma_f32_32x32x16_bf16 v[18:33], v[178:181], v[170:173], v[18:33]
	ds_read_b128 v[210:213], v81 offset:26624
	v_mfma_f32_32x32x16_bf16 v[2:17], v[178:181], v[174:177], v[2:17]
	ds_read_b128 v[222:225], v79 offset:26624
	s_waitcnt lgkmcnt(5)
	v_mfma_f32_32x32x16_bf16 v[94:109], v[182:185], v[170:173], v[94:109]
	ds_read_b128 v[236:239], v79 offset:32768
	v_mfma_f32_32x32x16_bf16 v[110:125], v[182:185], v[174:177], v[110:125]
	ds_read_b128 v[240:243], v79 offset:34816
	s_waitcnt lgkmcnt(6)
	v_mfma_f32_32x32x16_bf16 v[134:149], v[188:191], v[170:173], v[134:149]
	v_mfma_f32_32x32x16_bf16 v[150:165], v[188:191], v[174:177], v[150:165]
	s_waitcnt vmcnt(0) lgkmcnt(0)
	s_barrier
	v_mfma_f32_32x32x16_bf16 v[50:65], v[192:195], v[206:209], v[50:65]
	s_mov_b32 m0, vcc_lo
	ds_read_b128 v[166:169], v78 offset:49152
	global_load_lds_dwordx4 v[66:67], off
	v_mfma_f32_32x32x16_bf16 v[34:49], v[192:195], v[210:213], v[34:49]
	s_add_u32 m0, vcc_lo, 0x6000
	ds_read_b128 v[170:173], v80 offset:49152
	global_load_lds_dwordx4 v[126:127], off
	v_mfma_f32_32x32x16_bf16 v[18:33], v[222:225], v[206:209], v[18:33]
	s_add_u32 m0, vcc_lo, 0x400
	ds_read_b128 v[174:177], v80 offset:51200
	global_load_lds_dwordx4 v[68:69], off
	v_mfma_f32_32x32x16_bf16 v[2:17], v[222:225], v[210:213], v[2:17]
	s_add_u32 m0, vcc_lo, 0x6400
	ds_read_b128 v[178:181], v78 offset:51200
	global_load_lds_dwordx4 v[128:129], off
	v_mfma_f32_32x32x16_bf16 v[94:109], v[236:239], v[206:209], v[94:109]
	s_add_u32 m0, vcc_lo, 0x2000
	ds_read_b128 v[182:185], v78 offset:57344
	global_load_lds_dwordx4 v[70:71], off
	v_mfma_f32_32x32x16_bf16 v[110:125], v[236:239], v[210:213], v[110:125]
	s_add_u32 m0, vcc_lo, 0x8000
	ds_read_b128 v[188:191], v78 offset:59392
	global_load_lds_dwordx4 v[130:131], off
	v_mfma_f32_32x32x16_bf16 v[134:149], v[240:243], v[206:209], v[134:149]
	s_add_u32 m0, vcc_lo, 0x2400
	s_nop 0
	global_load_lds_dwordx4 v[72:73], off
	v_mfma_f32_32x32x16_bf16 v[150:165], v[240:243], v[210:213], v[150:165]
	s_add_u32 m0, vcc_lo, 0x8400
	s_nop 0
	global_load_lds_dwordx4 v[132:133], off
	s_waitcnt lgkmcnt(4)
	v_mfma_f32_32x32x16_bf16 v[50:65], v[166:169], v[170:173], v[50:65]
	s_add_u32 m0, vcc_lo, 0x4000
	ds_read_b128 v[192:195], v79 offset:49152
	global_load_lds_dwordx4 v[74:75], off
	s_waitcnt lgkmcnt(4)
	v_mfma_f32_32x32x16_bf16 v[34:49], v[166:169], v[174:177], v[34:49]
	s_add_u32 m0, vcc_lo, 0xa000
	ds_read_b128 v[206:209], v81 offset:49152
	global_load_lds_dwordx4 v[244:245], off
	s_waitcnt lgkmcnt(4)
	v_mfma_f32_32x32x16_bf16 v[18:33], v[178:181], v[170:173], v[18:33]
	s_add_u32 m0, vcc_lo, 0x4400
	ds_read_b128 v[210:213], v81 offset:51200
	global_load_lds_dwordx4 v[76:77], off
	v_mfma_f32_32x32x16_bf16 v[2:17], v[178:181], v[174:177], v[2:17]
	s_add_u32 m0, vcc_lo, 0xa400
	ds_read_b128 v[222:225], v79 offset:51200
	global_load_lds_dwordx4 v[246:247], off
	s_waitcnt lgkmcnt(5)
	v_mfma_f32_32x32x16_bf16 v[94:109], v[182:185], v[170:173], v[94:109]
	ds_read_b128 v[236:239], v79 offset:57344
	v_lshl_add_u64 v[66:67], v[66:67], 0, v[82:83]
	v_lshl_add_u64 v[68:69], v[68:69], 0, v[82:83]
	v_lshl_add_u64 v[70:71], v[70:71], 0, v[82:83]
	v_lshl_add_u64 v[72:73], v[72:73], 0, v[82:83]
	v_lshl_add_u64 v[74:75], v[74:75], 0, v[82:83]
	v_lshl_add_u64 v[76:77], v[76:77], 0, v[82:83]
	v_lshl_add_u64 v[126:127], v[126:127], 0, v[82:83]
	v_lshl_add_u64 v[128:129], v[128:129], 0, v[82:83]
	v_lshl_add_u64 v[130:131], v[130:131], 0, v[82:83]
	v_lshl_add_u64 v[132:133], v[132:133], 0, v[82:83]
	v_lshl_add_u64 v[244:245], v[244:245], 0, v[82:83]
	v_lshl_add_u64 v[246:247], v[246:247], 0, v[82:83]
	v_mfma_f32_32x32x16_bf16 v[110:125], v[182:185], v[174:177], v[110:125]
	ds_read_b128 v[240:243], v79 offset:59392
	s_waitcnt lgkmcnt(6)
	v_mfma_f32_32x32x16_bf16 v[134:149], v[188:191], v[170:173], v[134:149]
	v_mfma_f32_32x32x16_bf16 v[150:165], v[188:191], v[174:177], v[150:165]
	s_waitcnt vmcnt(0) lgkmcnt(0)
	s_barrier
	v_mfma_f32_32x32x16_bf16 v[50:65], v[192:195], v[206:209], v[50:65]
	ds_read_b128 v[166:169], v78
	v_mfma_f32_32x32x16_bf16 v[34:49], v[192:195], v[210:213], v[34:49]
	ds_read_b128 v[170:173], v80
	v_mfma_f32_32x32x16_bf16 v[18:33], v[222:225], v[206:209], v[18:33]
	ds_read_b128 v[174:177], v80 offset:2048
	v_mfma_f32_32x32x16_bf16 v[2:17], v[222:225], v[210:213], v[2:17]
	ds_read_b128 v[178:181], v78 offset:2048
	v_mfma_f32_32x32x16_bf16 v[94:109], v[236:239], v[206:209], v[94:109]
	ds_read_b128 v[182:185], v78 offset:8192
	v_mfma_f32_32x32x16_bf16 v[110:125], v[236:239], v[210:213], v[110:125]
	ds_read_b128 v[188:191], v78 offset:10240
	v_mfma_f32_32x32x16_bf16 v[134:149], v[240:243], v[206:209], v[134:149]
	v_mfma_f32_32x32x16_bf16 v[150:165], v[240:243], v[210:213], v[150:165]
	s_waitcnt lgkmcnt(4)
	v_mfma_f32_32x32x16_bf16 v[50:65], v[166:169], v[170:173], v[50:65]
	ds_read_b128 v[192:195], v79
	s_waitcnt lgkmcnt(4)
	v_mfma_f32_32x32x16_bf16 v[34:49], v[166:169], v[174:177], v[34:49]
	ds_read_b128 v[206:209], v81
	s_waitcnt lgkmcnt(4)
	v_mfma_f32_32x32x16_bf16 v[18:33], v[178:181], v[170:173], v[18:33]
	ds_read_b128 v[210:213], v81 offset:2048
	v_mfma_f32_32x32x16_bf16 v[2:17], v[178:181], v[174:177], v[2:17]
	ds_read_b128 v[222:225], v79 offset:2048
	s_waitcnt lgkmcnt(5)
	v_mfma_f32_32x32x16_bf16 v[94:109], v[182:185], v[170:173], v[94:109]
	ds_read_b128 v[236:239], v79 offset:8192
	v_mfma_f32_32x32x16_bf16 v[110:125], v[182:185], v[174:177], v[110:125]
	ds_read_b128 v[240:243], v79 offset:10240
	s_waitcnt lgkmcnt(6)
	v_mfma_f32_32x32x16_bf16 v[134:149], v[188:191], v[170:173], v[134:149]
	v_mfma_f32_32x32x16_bf16 v[150:165], v[188:191], v[174:177], v[150:165]
	s_waitcnt vmcnt(0) lgkmcnt(0)
	s_barrier
	s_sub_u32 vcc_hi, vcc_hi, 1
	s_cmp_lg_u32 vcc_hi, 0
	s_cbranch_scc1 .Lg_gemm1p_loop
	v_mfma_f32_32x32x16_bf16 v[50:65], v[192:195], v[206:209], v[50:65]
	s_add_u32 m0, vcc_lo, 0xc000
	ds_read_b128 v[166:169], v78 offset:24576
	global_load_lds_dwordx4 v[66:67], off
	v_mfma_f32_32x32x16_bf16 v[34:49], v[192:195], v[210:213], v[34:49]
	s_mov_b32 m0, vcc_lo
	ds_read_b128 v[170:173], v80 offset:24576
	global_load_lds_dwordx4 v[126:127], off
	v_mfma_f32_32x32x16_bf16 v[18:33], v[222:225], v[206:209], v[18:33]
	s_add_u32 m0, vcc_lo, 0xc400
	ds_read_b128 v[174:177], v80 offset:26624
	global_load_lds_dwordx4 v[68:69], off
	v_mfma_f32_32x32x16_bf16 v[2:17], v[222:225], v[210:213], v[2:17]
	s_add_u32 m0, vcc_lo, 0x400
	ds_read_b128 v[178:181], v78 offset:26624
	global_load_lds_dwordx4 v[128:129], off
	v_mfma_f32_32x32x16_bf16 v[94:109], v[236:239], v[206:209], v[94:109]
	s_add_u32 m0, vcc_lo, 0xe000
	ds_read_b128 v[182:185], v78 offset:32768
	global_load_lds_dwordx4 v[70:71], off
	v_mfma_f32_32x32x16_bf16 v[110:125], v[236:239], v[210:213], v[110:125]
	s_add_u32 m0, vcc_lo, 0x2000
	ds_read_b128 v[188:191], v78 offset:34816
	global_load_lds_dwordx4 v[130:131], off
	v_mfma_f32_32x32x16_bf16 v[134:149], v[240:243], v[206:209], v[134:149]
	s_add_u32 m0, vcc_lo, 0xe400
	s_nop 0
	global_load_lds_dwordx4 v[72:73], off
	v_mfma_f32_32x32x16_bf16 v[150:165], v[240:243], v[210:213], v[150:165]
	s_add_u32 m0, vcc_lo, 0x2400
	s_nop 0
	global_load_lds_dwordx4 v[132:133], off
	s_waitcnt lgkmcnt(4)
	v_mfma_f32_32x32x16_bf16 v[50:65], v[166:169], v[170:173], v[50:65]
	s_add_u32 m0, vcc_lo, 0x10000
	ds_read_b128 v[192:195], v79 offset:24576
	global_load_lds_dwordx4 v[74:75], off
	s_waitcnt lgkmcnt(4)
	v_mfma_f32_32x32x16_bf16 v[34:49], v[166:169], v[174:177], v[34:49]
	s_add_u32 m0, vcc_lo, 0x4000
	ds_read_b128 v[206:209], v81 offset:24576
	global_load_lds_dwordx4 v[244:245], off
	s_waitcnt lgkmcnt(4)
	v_mfma_f32_32x32x16_bf16 v[18:33], v[178:181], v[170:173], v[18:33]
	s_add_u32 m0, vcc_lo, 0x10400
	ds_read_b128 v[210:213], v81 offset:26624
	global_load_lds_dwordx4 v[76:77], off
	v_mfma_f32_32x32x16_bf16 v[2:17], v[178:181], v[174:177], v[2:17]
	s_add_u32 m0, vcc_lo, 0x4400
	ds_read_b128 v[222:225], v79 offset:26624
	global_load_lds_dwordx4 v[246:247], off
	s_waitcnt lgkmcnt(5)
	v_mfma_f32_32x32x16_bf16 v[94:109], v[182:185], v[170:173], v[94:109]
	ds_read_b128 v[236:239], v79 offset:32768
	v_lshl_add_u64 v[66:67], v[66:67], 0, v[82:83]
	v_lshl_add_u64 v[68:69], v[68:69], 0, v[82:83]
	v_lshl_add_u64 v[70:71], v[70:71], 0, v[82:83]
	v_lshl_add_u64 v[72:73], v[72:73], 0, v[82:83]
	v_lshl_add_u64 v[74:75], v[74:75], 0, v[82:83]
	v_lshl_add_u64 v[76:77], v[76:77], 0, v[82:83]
	v_lshl_add_u64 v[126:127], v[126:127], 0, v[82:83]
	v_lshl_add_u64 v[128:129], v[128:129], 0, v[82:83]
	v_lshl_add_u64 v[130:131], v[130:131], 0, v[82:83]
	v_lshl_add_u64 v[132:133], v[132:133], 0, v[82:83]
	v_lshl_add_u64 v[244:245], v[244:245], 0, v[82:83]
	v_lshl_add_u64 v[246:247], v[246:247], 0, v[82:83]
	v_mfma_f32_32x32x16_bf16 v[110:125], v[182:185], v[174:177], v[110:125]
	ds_read_b128 v[240:243], v79 offset:34816
	s_waitcnt lgkmcnt(6)
	v_mfma_f32_32x32x16_bf16 v[134:149], v[188:191], v[170:173], v[134:149]
	v_mfma_f32_32x32x16_bf16 v[150:165], v[188:191], v[174:177], v[150:165]
	s_waitcnt vmcnt(0) lgkmcnt(0)
	s_barrier
	v_mfma_f32_32x32x16_bf16 v[50:65], v[192:195], v[206:209], v[50:65]
	ds_read_b128 v[166:169], v78 offset:49152
	v_mfma_f32_32x32x16_bf16 v[34:49], v[192:195], v[210:213], v[34:49]
	ds_read_b128 v[170:173], v80 offset:49152
	v_mfma_f32_32x32x16_bf16 v[18:33], v[222:225], v[206:209], v[18:33]
	ds_read_b128 v[174:177], v80 offset:51200
	v_mfma_f32_32x32x16_bf16 v[2:17], v[222:225], v[210:213], v[2:17]
	ds_read_b128 v[178:181], v78 offset:51200
	v_mfma_f32_32x32x16_bf16 v[94:109], v[236:239], v[206:209], v[94:109]
	ds_read_b128 v[182:185], v78 offset:57344
	v_mfma_f32_32x32x16_bf16 v[110:125], v[236:239], v[210:213], v[110:125]
	ds_read_b128 v[188:191], v78 offset:59392
	v_mfma_f32_32x32x16_bf16 v[134:149], v[240:243], v[206:209], v[134:149]
	v_mfma_f32_32x32x16_bf16 v[150:165], v[240:243], v[210:213], v[150:165]
	s_waitcnt lgkmcnt(4)
	v_mfma_f32_32x32x16_bf16 v[50:65], v[166:169], v[170:173], v[50:65]
	ds_read_b128 v[192:195], v79 offset:49152
	s_waitcnt lgkmcnt(4)
	v_mfma_f32_32x32x16_bf16 v[34:49], v[166:169], v[174:177], v[34:49]
	ds_read_b128 v[206:209], v81 offset:49152
	s_waitcnt lgkmcnt(4)
	v_mfma_f32_32x32x16_bf16 v[18:33], v[178:181], v[170:173], v[18:33]
	ds_read_b128 v[210:213], v81 offset:51200
	v_mfma_f32_32x32x16_bf16 v[2:17], v[178:181], v[174:177], v[2:17]
	ds_read_b128 v[222:225], v79 offset:51200
	s_waitcnt lgkmcnt(5)
	v_mfma_f32_32x32x16_bf16 v[94:109], v[182:185], v[170:173], v[94:109]
	ds_read_b128 v[236:239], v79 offset:57344
	v_mfma_f32_32x32x16_bf16 v[110:125], v[182:185], v[174:177], v[110:125]
	ds_read_b128 v[240:243], v79 offset:59392
	s_waitcnt lgkmcnt(6)
	v_mfma_f32_32x32x16_bf16 v[134:149], v[188:191], v[170:173], v[134:149]
	v_mfma_f32_32x32x16_bf16 v[150:165], v[188:191], v[174:177], v[150:165]
	s_waitcnt vmcnt(0) lgkmcnt(0)
	s_barrier
	v_mfma_f32_32x32x16_bf16 v[50:65], v[192:195], v[206:209], v[50:65]
	s_add_u32 m0, vcc_lo, 0x6000
	ds_read_b128 v[166:169], v78
	global_load_lds_dwordx4 v[66:67], off
	v_mfma_f32_32x32x16_bf16 v[34:49], v[192:195], v[210:213], v[34:49]
	s_add_u32 m0, vcc_lo, 0xc000
	ds_read_b128 v[170:173], v80
	global_load_lds_dwordx4 v[126:127], off
	v_mfma_f32_32x32x16_bf16 v[18:33], v[222:225], v[206:209], v[18:33]
	s_add_u32 m0, vcc_lo, 0x6400
	ds_read_b128 v[174:177], v80 offset:2048
	global_load_lds_dwordx4 v[68:69], off
	v_mfma_f32_32x32x16_bf16 v[2:17], v[222:225], v[210:213], v[2:17]
	s_add_u32 m0, vcc_lo, 0xc400
	ds_read_b128 v[178:181], v78 offset:2048
	global_load_lds_dwordx4 v[128:129], off
	v_mfma_f32_32x32x16_bf16 v[94:109], v[236:239], v[206:209], v[94:109]
	s_add_u32 m0, vcc_lo, 0x8000
	ds_read_b128 v[182:185], v78 offset:8192
	global_load_lds_dwordx4 v[70:71], off
	v_mfma_f32_32x32x16_bf16 v[110:125], v[236:239], v[210:213], v[110:125]
	s_add_u32 m0, vcc_lo, 0xe000
	ds_read_b128 v[188:191], v78 offset:10240
	global_load_lds_dwordx4 v[130:131], off
	v_mfma_f32_32x32x16_bf16 v[134:149], v[240:243], v[206:209], v[134:149]
	s_add_u32 m0, vcc_lo, 0x8400
	s_nop 0
	global_load_lds_dwordx4 v[72:73], off
	v_mfma_f32_32x32x16_bf16 v[150:165], v[240:243], v[210:213], v[150:165]
	s_add_u32 m0, vcc_lo, 0xe400
	s_nop 0
	global_load_lds_dwordx4 v[132:133], off
	s_waitcnt lgkmcnt(4)
	v_mfma_f32_32x32x16_bf16 v[50:65], v[166:169], v[170:173], v[50:65]
	s_add_u32 m0, vcc_lo, 0xa000
	ds_read_b128 v[192:195], v79
	global_load_lds_dwordx4 v[74:75], off
	s_waitcnt lgkmcnt(4)
	v_mfma_f32_32x32x16_bf16 v[34:49], v[166:169], v[174:177], v[34:49]
	s_add_u32 m0, vcc_lo, 0x10000
	ds_read_b128 v[206:209], v81
	global_load_lds_dwordx4 v[244:245], off
	s_waitcnt lgkmcnt(4)
	v_mfma_f32_32x32x16_bf16 v[18:33], v[178:181], v[170:173], v[18:33]
	s_add_u32 m0, vcc_lo, 0xa400
	ds_read_b128 v[210:213], v81 offset:2048
	global_load_lds_dwordx4 v[76:77], off
	v_mfma_f32_32x32x16_bf16 v[2:17], v[178:181], v[174:177], v[2:17]
	s_add_u32 m0, vcc_lo, 0x10400
	ds_read_b128 v[222:225], v79 offset:2048
	global_load_lds_dwordx4 v[246:247], off
	s_waitcnt lgkmcnt(5)
	v_mfma_f32_32x32x16_bf16 v[94:109], v[182:185], v[170:173], v[94:109]
	ds_read_b128 v[236:239], v79 offset:8192
	v_lshl_add_u64 v[66:67], v[66:67], 0, v[82:83]
	v_lshl_add_u64 v[68:69], v[68:69], 0, v[82:83]
	v_lshl_add_u64 v[70:71], v[70:71], 0, v[82:83]
	v_lshl_add_u64 v[72:73], v[72:73], 0, v[82:83]
	v_lshl_add_u64 v[74:75], v[74:75], 0, v[82:83]
	v_lshl_add_u64 v[76:77], v[76:77], 0, v[82:83]
	v_lshl_add_u64 v[126:127], v[126:127], 0, v[82:83]
	v_lshl_add_u64 v[128:129], v[128:129], 0, v[82:83]
	v_lshl_add_u64 v[130:131], v[130:131], 0, v[82:83]
	v_lshl_add_u64 v[132:133], v[132:133], 0, v[82:83]
	v_lshl_add_u64 v[244:245], v[244:245], 0, v[82:83]
	v_lshl_add_u64 v[246:247], v[246:247], 0, v[82:83]
	v_mfma_f32_32x32x16_bf16 v[110:125], v[182:185], v[174:177], v[110:125]
	ds_read_b128 v[240:243], v79 offset:10240
	s_waitcnt lgkmcnt(6)
	v_mfma_f32_32x32x16_bf16 v[134:149], v[188:191], v[170:173], v[134:149]
	v_mfma_f32_32x32x16_bf16 v[150:165], v[188:191], v[174:177], v[150:165]
	s_waitcnt vmcnt(0) lgkmcnt(0)
	s_barrier
	v_mfma_f32_32x32x16_bf16 v[50:65], v[192:195], v[206:209], v[50:65]
	ds_read_b128 v[166:169], v78 offset:24576
	v_mfma_f32_32x32x16_bf16 v[34:49], v[192:195], v[210:213], v[34:49]
	ds_read_b128 v[170:173], v80 offset:24576
	v_mfma_f32_32x32x16_bf16 v[18:33], v[222:225], v[206:209], v[18:33]
	ds_read_b128 v[174:177], v80 offset:26624
	v_mfma_f32_32x32x16_bf16 v[2:17], v[222:225], v[210:213], v[2:17]
	ds_read_b128 v[178:181], v78 offset:26624
	v_mfma_f32_32x32x16_bf16 v[94:109], v[236:239], v[206:209], v[94:109]
	ds_read_b128 v[182:185], v78 offset:32768
	v_mfma_f32_32x32x16_bf16 v[110:125], v[236:239], v[210:213], v[110:125]
	ds_read_b128 v[188:191], v78 offset:34816
	v_mfma_f32_32x32x16_bf16 v[134:149], v[240:243], v[206:209], v[134:149]
	v_mfma_f32_32x32x16_bf16 v[150:165], v[240:243], v[210:213], v[150:165]
	s_waitcnt lgkmcnt(4)
	v_mfma_f32_32x32x16_bf16 v[50:65], v[166:169], v[170:173], v[50:65]
	ds_read_b128 v[192:195], v79 offset:24576
	s_waitcnt lgkmcnt(4)
	v_mfma_f32_32x32x16_bf16 v[34:49], v[166:169], v[174:177], v[34:49]
	ds_read_b128 v[206:209], v81 offset:24576
	s_waitcnt lgkmcnt(4)
	v_mfma_f32_32x32x16_bf16 v[18:33], v[178:181], v[170:173], v[18:33]
	ds_read_b128 v[210:213], v81 offset:26624
	v_mfma_f32_32x32x16_bf16 v[2:17], v[178:181], v[174:177], v[2:17]
	ds_read_b128 v[222:225], v79 offset:26624
	s_waitcnt lgkmcnt(5)
	v_mfma_f32_32x32x16_bf16 v[94:109], v[182:185], v[170:173], v[94:109]
	ds_read_b128 v[236:239], v79 offset:32768
	v_mfma_f32_32x32x16_bf16 v[110:125], v[182:185], v[174:177], v[110:125]
	ds_read_b128 v[240:243], v79 offset:34816
	s_waitcnt lgkmcnt(6)
	v_mfma_f32_32x32x16_bf16 v[134:149], v[188:191], v[170:173], v[134:149]
	v_mfma_f32_32x32x16_bf16 v[150:165], v[188:191], v[174:177], v[150:165]
	s_waitcnt vmcnt(0) lgkmcnt(0)
	s_barrier
	v_mfma_f32_32x32x16_bf16 v[50:65], v[192:195], v[206:209], v[50:65]
	s_mov_b32 m0, vcc_lo
	ds_read_b128 v[166:169], v78 offset:49152
	global_load_lds_dwordx4 v[66:67], off
	v_mfma_f32_32x32x16_bf16 v[34:49], v[192:195], v[210:213], v[34:49]
	s_add_u32 m0, vcc_lo, 0x6000
	ds_read_b128 v[170:173], v80 offset:49152
	global_load_lds_dwordx4 v[126:127], off
	v_mfma_f32_32x32x16_bf16 v[18:33], v[222:225], v[206:209], v[18:33]
	s_add_u32 m0, vcc_lo, 0x400
	ds_read_b128 v[174:177], v80 offset:51200
	global_load_lds_dwordx4 v[68:69], off
	v_mfma_f32_32x32x16_bf16 v[2:17], v[222:225], v[210:213], v[2:17]
	s_add_u32 m0, vcc_lo, 0x6400
	ds_read_b128 v[178:181], v78 offset:51200
	global_load_lds_dwordx4 v[128:129], off
	v_mfma_f32_32x32x16_bf16 v[94:109], v[236:239], v[206:209], v[94:109]
	s_add_u32 m0, vcc_lo, 0x2000
	ds_read_b128 v[182:185], v78 offset:57344
	global_load_lds_dwordx4 v[70:71], off
	v_mfma_f32_32x32x16_bf16 v[110:125], v[236:239], v[210:213], v[110:125]
	s_add_u32 m0, vcc_lo, 0x8000
	ds_read_b128 v[188:191], v78 offset:59392
	global_load_lds_dwordx4 v[130:131], off
	v_mfma_f32_32x32x16_bf16 v[134:149], v[240:243], v[206:209], v[134:149]
	s_add_u32 m0, vcc_lo, 0x2400
	s_nop 0
	global_load_lds_dwordx4 v[72:73], off
	v_mfma_f32_32x32x16_bf16 v[150:165], v[240:243], v[210:213], v[150:165]
	s_add_u32 m0, vcc_lo, 0x8400
	s_nop 0
	global_load_lds_dwordx4 v[132:133], off
	s_waitcnt lgkmcnt(4)
	v_mfma_f32_32x32x16_bf16 v[50:65], v[166:169], v[170:173], v[50:65]
	s_add_u32 m0, vcc_lo, 0x4000
	ds_read_b128 v[192:195], v79 offset:49152
	global_load_lds_dwordx4 v[74:75], off
	s_waitcnt lgkmcnt(4)
	v_mfma_f32_32x32x16_bf16 v[34:49], v[166:169], v[174:177], v[34:49]
	s_add_u32 m0, vcc_lo, 0xa000
	ds_read_b128 v[206:209], v81 offset:49152
	global_load_lds_dwordx4 v[244:245], off
	s_waitcnt lgkmcnt(4)
	v_mfma_f32_32x32x16_bf16 v[18:33], v[178:181], v[170:173], v[18:33]
	s_add_u32 m0, vcc_lo, 0x4400
	ds_read_b128 v[210:213], v81 offset:51200
	global_load_lds_dwordx4 v[76:77], off
	v_mfma_f32_32x32x16_bf16 v[2:17], v[178:181], v[174:177], v[2:17]
	s_add_u32 m0, vcc_lo, 0xa400
	ds_read_b128 v[222:225], v79 offset:51200
	global_load_lds_dwordx4 v[246:247], off
	s_waitcnt lgkmcnt(5)
	v_mfma_f32_32x32x16_bf16 v[94:109], v[182:185], v[170:173], v[94:109]
	ds_read_b128 v[236:239], v79 offset:57344
	v_lshl_add_u64 v[66:67], v[66:67], 0, v[82:83]
	v_lshl_add_u64 v[68:69], v[68:69], 0, v[82:83]
	v_lshl_add_u64 v[70:71], v[70:71], 0, v[82:83]
	v_lshl_add_u64 v[72:73], v[72:73], 0, v[82:83]
	v_lshl_add_u64 v[74:75], v[74:75], 0, v[82:83]
	v_lshl_add_u64 v[76:77], v[76:77], 0, v[82:83]
	v_lshl_add_u64 v[126:127], v[126:127], 0, v[82:83]
	v_lshl_add_u64 v[128:129], v[128:129], 0, v[82:83]
	v_lshl_add_u64 v[130:131], v[130:131], 0, v[82:83]
	v_lshl_add_u64 v[132:133], v[132:133], 0, v[82:83]
	v_lshl_add_u64 v[244:245], v[244:245], 0, v[82:83]
	v_lshl_add_u64 v[246:247], v[246:247], 0, v[82:83]
	v_mfma_f32_32x32x16_bf16 v[110:125], v[182:185], v[174:177], v[110:125]
	ds_read_b128 v[240:243], v79 offset:59392
	s_waitcnt lgkmcnt(6)
	v_mfma_f32_32x32x16_bf16 v[134:149], v[188:191], v[170:173], v[134:149]
	v_mfma_f32_32x32x16_bf16 v[150:165], v[188:191], v[174:177], v[150:165]
	s_waitcnt vmcnt(0) lgkmcnt(0)
	s_barrier
	v_mfma_f32_32x32x16_bf16 v[50:65], v[192:195], v[206:209], v[50:65]
	ds_read_b128 v[166:169], v78
	v_mfma_f32_32x32x16_bf16 v[34:49], v[192:195], v[210:213], v[34:49]
	ds_read_b128 v[170:173], v80
	v_mfma_f32_32x32x16_bf16 v[18:33], v[222:225], v[206:209], v[18:33]
	ds_read_b128 v[174:177], v80 offset:2048
	v_mfma_f32_32x32x16_bf16 v[2:17], v[222:225], v[210:213], v[2:17]
	ds_read_b128 v[178:181], v78 offset:2048
	v_mfma_f32_32x32x16_bf16 v[94:109], v[236:239], v[206:209], v[94:109]
	ds_read_b128 v[182:185], v78 offset:8192
	v_mfma_f32_32x32x16_bf16 v[110:125], v[236:239], v[210:213], v[110:125]
	ds_read_b128 v[188:191], v78 offset:10240
	v_mfma_f32_32x32x16_bf16 v[134:149], v[240:243], v[206:209], v[134:149]
	v_mfma_f32_32x32x16_bf16 v[150:165], v[240:243], v[210:213], v[150:165]
	s_waitcnt lgkmcnt(4)
	v_mfma_f32_32x32x16_bf16 v[50:65], v[166:169], v[170:173], v[50:65]
	ds_read_b128 v[192:195], v79
	s_waitcnt lgkmcnt(4)
	v_mfma_f32_32x32x16_bf16 v[34:49], v[166:169], v[174:177], v[34:49]
	ds_read_b128 v[206:209], v81
	s_waitcnt lgkmcnt(4)
	v_mfma_f32_32x32x16_bf16 v[18:33], v[178:181], v[170:173], v[18:33]
	ds_read_b128 v[210:213], v81 offset:2048
	v_mfma_f32_32x32x16_bf16 v[2:17], v[178:181], v[174:177], v[2:17]
	ds_read_b128 v[222:225], v79 offset:2048
	s_waitcnt lgkmcnt(5)
	v_mfma_f32_32x32x16_bf16 v[94:109], v[182:185], v[170:173], v[94:109]
	ds_read_b128 v[236:239], v79 offset:8192
	v_mfma_f32_32x32x16_bf16 v[110:125], v[182:185], v[174:177], v[110:125]
	ds_read_b128 v[240:243], v79 offset:10240
	s_waitcnt lgkmcnt(6)
	v_mfma_f32_32x32x16_bf16 v[134:149], v[188:191], v[170:173], v[134:149]
	v_mfma_f32_32x32x16_bf16 v[150:165], v[188:191], v[174:177], v[150:165]
	s_waitcnt vmcnt(0) lgkmcnt(0)
	s_barrier
	v_mfma_f32_32x32x16_bf16 v[50:65], v[192:195], v[206:209], v[50:65]
	ds_read_b128 v[166:169], v78 offset:24576
	v_mfma_f32_32x32x16_bf16 v[34:49], v[192:195], v[210:213], v[34:49]
	ds_read_b128 v[170:173], v80 offset:24576
	v_mfma_f32_32x32x16_bf16 v[18:33], v[222:225], v[206:209], v[18:33]
	ds_read_b128 v[174:177], v80 offset:26624
	v_mfma_f32_32x32x16_bf16 v[2:17], v[222:225], v[210:213], v[2:17]
	ds_read_b128 v[178:181], v78 offset:26624
	v_mfma_f32_32x32x16_bf16 v[94:109], v[236:239], v[206:209], v[94:109]
	ds_read_b128 v[182:185], v78 offset:32768
	v_mfma_f32_32x32x16_bf16 v[110:125], v[236:239], v[210:213], v[110:125]
	ds_read_b128 v[188:191], v78 offset:34816
	v_mfma_f32_32x32x16_bf16 v[134:149], v[240:243], v[206:209], v[134:149]
	v_mfma_f32_32x32x16_bf16 v[150:165], v[240:243], v[210:213], v[150:165]
	s_waitcnt lgkmcnt(4)
	v_mfma_f32_32x32x16_bf16 v[50:65], v[166:169], v[170:173], v[50:65]
	ds_read_b128 v[192:195], v79 offset:24576
	s_waitcnt lgkmcnt(4)
	v_mfma_f32_32x32x16_bf16 v[34:49], v[166:169], v[174:177], v[34:49]
	ds_read_b128 v[206:209], v81 offset:24576
	s_waitcnt lgkmcnt(4)
	v_mfma_f32_32x32x16_bf16 v[18:33], v[178:181], v[170:173], v[18:33]
	ds_read_b128 v[210:213], v81 offset:26624
	v_mfma_f32_32x32x16_bf16 v[2:17], v[178:181], v[174:177], v[2:17]
	ds_read_b128 v[222:225], v79 offset:26624
	s_waitcnt lgkmcnt(5)
	v_mfma_f32_32x32x16_bf16 v[94:109], v[182:185], v[170:173], v[94:109]
	ds_read_b128 v[236:239], v79 offset:32768
	v_mfma_f32_32x32x16_bf16 v[110:125], v[182:185], v[174:177], v[110:125]
	ds_read_b128 v[240:243], v79 offset:34816
	s_waitcnt lgkmcnt(6)
	v_mfma_f32_32x32x16_bf16 v[134:149], v[188:191], v[170:173], v[134:149]
	v_mfma_f32_32x32x16_bf16 v[150:165], v[188:191], v[174:177], v[150:165]
	s_waitcnt lgkmcnt(4)
	v_mfma_f32_32x32x16_bf16 v[50:65], v[192:195], v[206:209], v[50:65]
	s_waitcnt lgkmcnt(3)
	v_mfma_f32_32x32x16_bf16 v[34:49], v[192:195], v[210:213], v[34:49]
	s_waitcnt lgkmcnt(2)
	v_mfma_f32_32x32x16_bf16 v[18:33], v[222:225], v[206:209], v[18:33]
	v_mfma_f32_32x32x16_bf16 v[2:17], v[222:225], v[210:213], v[2:17]
	s_waitcnt lgkmcnt(1)
	v_mfma_f32_32x32x16_bf16 v[94:109], v[236:239], v[206:209], v[94:109]
	v_mfma_f32_32x32x16_bf16 v[110:125], v[236:239], v[210:213], v[110:125]
	s_waitcnt lgkmcnt(0)
	v_mfma_f32_32x32x16_bf16 v[134:149], v[240:243], v[206:209], v[134:149]
	v_mfma_f32_32x32x16_bf16 v[150:165], v[240:243], v[210:213], v[150:165]
	s_nop 7
	s_nop 7
	s_mov_b32 m0, 0x7ead
.Lg1p_epi:
	s_cmpk_lt_u32 s28, 0x400
	s_movk_i32 s29, 0x400
	s_barrier
	s_cbranch_scc1 .LBB0_522
	s_cmpk_gt_u32 s28, 0xdff
	s_mov_b64 s[22:23], -1
	s_cbranch_scc0 .LBB0_520
	s_cmpk_gt_u32 s28, 0x13ff
	s_mov_b64 s[20:21], -1
	s_cbranch_scc0 .LBB0_517
	s_add_i32 s30, s28, 0xffffec00
	s_mov_b64 s[20:21], 0
